# EpiResid + P3 EpiScale epilogues: loads hoisted above the barrier, batched row-sum shuffles
# baseline (speedup 1.0000x reference)
; #define PG8_STAGE(bufoff, gbase, voff) do { _Pragma("unroll") for (int _i = 0; _i < 2; ++_i) \
;         __builtin_amdgcn_global_load_lds((const unsigned*)((const char*)(gbase) + (voff)[_i]), (PG8_LAS unsigned*)(lds + (bufoff) + ldsw + _i * 8192), 16, 0, 0); } while (0)
; #define PG8_LDA(dst, b, h) do { _Pragma("unroll") for (int m = 0; m < 4; ++m) _Pragma("unroll") for (int k = 0; k < 2; ++k) dst[m][k] = *(const PG8_LAS bf16x8*)(lds + PG8_SA(b, h) + aoff + m * 2048 + k * 1024); } while (0)
; #define PG8_LDB(dst, b, h) do { _Pragma("unroll") for (int n = 0; n < 2; ++n) _Pragma("unroll") for (int k = 0; k < 2; ++k) dst[n][k] = *(const PG8_LAS bf16x8*)(lds + PG8_SB(b, h) + boff + n * 2048 + k * 1024); } while (0)
; #define PG8_MMA(ai, bj, At, Bt) do { __builtin_amdgcn_s_setprio(1); _Pragma("unroll") for (int m = 0; m < 4; ++m) _Pragma("unroll") for (int n = 0; n < 2; ++n) _Pragma("unroll") for (int k = 0; k < 2; ++k) \
;         acc[ai][bj][m][n] = __builtin_amdgcn_mfma_f32_16x16x32_bf16(Bt[n][k], At[m][k], acc[ai][bj][m][n], 0, 0, 0); __builtin_amdgcn_s_setprio(0); } while (0)
; #define PG8_WAIT_V(n) asm volatile("s_waitcnt vmcnt(" #n ")" ::: "memory")
; #define PG8_WAIT_L(n) asm volatile("s_waitcnt lgkmcnt(" #n ")" ::: "memory")
; #define PG8_BAR __builtin_amdgcn_s_barrier()
; #define PG8_SCHED __builtin_amdgcn_sched_barrier(0)
; template <class Epi, class Sched, bool ALIGN_EPI = false, bool SP2 = false>
; __device__ __forceinline__ void gemm_phase(PG8_LAS unsigned char* lds, const Gemm g, const Sched& S, const Epi& E) {
;     ...
;         for (int t = 0; t < nt; t += 2) {
;             const bool last = (t == nt - 2);
;             const char* a1 = cA + (size_t)(t + 1) * kstep;
;             const char* a2 = last ? nA : cA + (size_t)(t + 2) * kstep; const char* b2 = last ? nB : cB + (size_t)(t + 2) * kstep;
;             const char* a3 = a2 + kstep; const char* b3 = b2 + kstep;
;             if (last && has_next) S.a_ready(nxt);
;             if constexpr (SP2) {
;             PG8_LDB(B0, 0, 0); PG8_LDB(B1, 0, 1); PG8_SCHED; PG8_LDA(At, 0, 0); PG8_STAGE(PG8_SA(1, 1), a1 + hstep, voffA);
;             PG8_WAIT_V(8); PG8_WAIT_L(0); PG8_BAR; PG8_MMA(0, 0, At, B0); PG8_MMA(0, 1, At, B1); PG8_BAR; PG8_SCHED;
;             PG8_LDA(At, 0, 1); PG8_STAGE(PG8_SB(0, 0), b2, voffB); PG8_STAGE(PG8_SB(0, 1), b2 + hstep, voffB); PG8_STAGE(PG8_SA(0, 0), a2, voffA);
.LBB0_165:
	s_add_u32 s68, s42, 0xfff80080
	s_addc_u32 s69, s43, -1
	s_add_i32 s82, 0, 0x10000
	s_cmp_eq_u32 s71, 28
	s_cselect_b32 s81, s47, s69
	s_cselect_b32 s80, s55, s68
	v_add_u32_e32 v144, s82, v147
	s_cselect_b32 s79, s45, s63
	s_cselect_b32 s78, s58, s59
	s_add_i32 s83, 0, 0x14000
	ds_read_b128 v[140:143], v144
	ds_read_b128 v[156:159], v144 offset:1024
	ds_read_b128 v[160:163], v144 offset:2048
	ds_read_b128 v[164:167], v144 offset:3072
	v_add_u32_e32 v144, s83, v147
	ds_read_b128 v[168:171], v144
	ds_read_b128 v[172:175], v144 offset:1024
	ds_read_b128 v[192:195], v144 offset:2048
	ds_read_b128 v[196:199], v144 offset:3072
	v_lshl_add_u64 v[150:151], s[42:43], 0, v[136:137]
	s_add_i32 m0, s14, 0xc000
	ds_read_b128 v[200:203], v149
	ds_read_b128 v[204:207], v149 offset:1024
	ds_read_b128 v[208:211], v149 offset:2048
	ds_read_b128 v[212:215], v149 offset:3072
	ds_read_b128 v[216:219], v149 offset:4096
	ds_read_b128 v[220:223], v149 offset:5120
	ds_read_b128 v[224:227], v149 offset:6144
	ds_read_b128 v[228:231], v149 offset:7168
	global_load_lds_dwordx4 v[150:151], off
	v_lshl_add_u64 v[150:151], s[42:43], 0, v[138:139]
	s_add_i32 m0, s14, 0xe000
	s_nop 0
	global_load_lds_dwordx4 v[150:151], off
	s_waitcnt vmcnt(8)
	s_waitcnt lgkmcnt(0)
	s_barrier
	s_setprio 1
	s_waitcnt lgkmcnt(0)
	v_mfma_f32_16x16x32_bf16 v[124:127], v[140:143], v[200:203], v[124:127]
	v_mfma_f32_16x16x32_bf16 v[120:123], v[160:163], v[200:203], v[120:123]
	v_mfma_f32_16x16x32_bf16 v[108:111], v[140:143], v[208:211], v[108:111]
	v_mfma_f32_16x16x32_bf16 v[104:107], v[160:163], v[208:211], v[104:107]
	v_mfma_f32_16x16x32_bf16 v[92:95], v[140:143], v[216:219], v[92:95]
	v_mfma_f32_16x16x32_bf16 v[88:91], v[160:163], v[216:219], v[88:91]
	v_mfma_f32_16x16x32_bf16 v[76:79], v[140:143], v[224:227], v[76:79]
	v_mfma_f32_16x16x32_bf16 v[72:75], v[160:163], v[224:227], v[72:75]
	v_mfma_f32_16x16x32_bf16 v[124:127], v[156:159], v[204:207], v[124:127]
	v_mfma_f32_16x16x32_bf16 v[120:123], v[164:167], v[204:207], v[120:123]
	v_mfma_f32_16x16x32_bf16 v[108:111], v[156:159], v[212:215], v[108:111]
	v_mfma_f32_16x16x32_bf16 v[104:107], v[164:167], v[212:215], v[104:107]
	v_mfma_f32_16x16x32_bf16 v[92:95], v[156:159], v[220:223], v[92:95]
	v_mfma_f32_16x16x32_bf16 v[88:91], v[164:167], v[220:223], v[88:91]
	v_mfma_f32_16x16x32_bf16 v[76:79], v[156:159], v[228:231], v[76:79]
	v_mfma_f32_16x16x32_bf16 v[72:75], v[164:167], v[228:231], v[72:75]
	s_setprio 0
	s_setprio 1
	v_mfma_f32_16x16x32_bf16 v[116:119], v[168:171], v[200:203], v[116:119]
	v_mfma_f32_16x16x32_bf16 v[112:115], v[192:195], v[200:203], v[112:115]
	v_mfma_f32_16x16x32_bf16 v[100:103], v[168:171], v[208:211], v[100:103]
	v_mfma_f32_16x16x32_bf16 v[96:99], v[192:195], v[208:211], v[96:99]
	v_mfma_f32_16x16x32_bf16 v[84:87], v[168:171], v[216:219], v[84:87]
	v_mfma_f32_16x16x32_bf16 v[80:83], v[192:195], v[216:219], v[80:83]
	v_mfma_f32_16x16x32_bf16 v[68:71], v[168:171], v[224:227], v[68:71]
	v_mfma_f32_16x16x32_bf16 v[64:67], v[192:195], v[224:227], v[64:67]
	v_mfma_f32_16x16x32_bf16 v[116:119], v[172:175], v[204:207], v[116:119]
	v_mfma_f32_16x16x32_bf16 v[112:115], v[196:199], v[204:207], v[112:115]
	v_mfma_f32_16x16x32_bf16 v[100:103], v[172:175], v[212:215], v[100:103]
	v_mfma_f32_16x16x32_bf16 v[96:99], v[196:199], v[212:215], v[96:99]
	v_mfma_f32_16x16x32_bf16 v[84:87], v[172:175], v[220:223], v[84:87]
	v_mfma_f32_16x16x32_bf16 v[80:83], v[196:199], v[220:223], v[80:83]
	v_mfma_f32_16x16x32_bf16 v[68:71], v[172:175], v[228:231], v[68:71]
	v_mfma_f32_16x16x32_bf16 v[64:67], v[196:199], v[228:231], v[64:67]
	s_setprio 0
	s_barrier
	s_add_i32 s68, s82, s0
	v_lshl_add_u64 v[150:151], s[78:79], 0, v[152:153]
	s_mov_b32 m0, s68
	ds_read_b128 v[200:203], v149 offset:16384
	ds_read_b128 v[204:207], v149 offset:17408
	ds_read_b128 v[208:211], v149 offset:18432
	ds_read_b128 v[212:215], v149 offset:19456
	ds_read_b128 v[216:219], v149 offset:20480
	ds_read_b128 v[220:223], v149 offset:21504
	ds_read_b128 v[224:227], v149 offset:22528
	ds_read_b128 v[228:231], v149 offset:23552
	global_load_lds_dwordx4 v[150:151], off
	s_add_i32 m0, s68, 0x2000
	s_add_u32 s68, s78, 0x80000
	v_lshl_add_u64 v[182:183], s[78:79], 0, v[128:129]
	s_addc_u32 s69, s79, 0
	s_add_i32 s82, s83, s0
	global_load_lds_dwordx4 v[182:183], off
	v_lshl_add_u64 v[184:185], s[68:69], 0, v[152:153]
	s_mov_b32 m0, s82
	v_lshl_add_u64 v[188:189], s[80:81], 0, v[130:131]
	global_load_lds_dwordx4 v[184:185], off
	v_lshl_add_u64 v[184:185], s[68:69], 0, v[128:129]
	s_add_i32 m0, s82, 0x2000
	s_nop 0
	global_load_lds_dwordx4 v[184:185], off
	v_lshl_add_u64 v[184:185], s[80:81], 0, v[132:133]
	s_mov_b32 m0, s14
	s_nop 0
	global_load_lds_dwordx4 v[184:185], off
	s_mov_b32 m0, s15
	s_nop 0
	global_load_lds_dwordx4 v[188:189], off
	s_waitcnt vmcnt(8)
	s_waitcnt lgkmcnt(0)
	s_barrier
; #define PG8_STAGE(bufoff, gbase, voff) do { _Pragma("unroll") for (int _i = 0; _i < 2; ++_i) \
;         __builtin_amdgcn_global_load_lds((const unsigned*)((const char*)(gbase) + (voff)[_i]), (PG8_LAS unsigned*)(lds + (bufoff) + ldsw + _i * 8192), 16, 0, 0); } while (0)
; #define PG8_LDA(dst, b, h) do { _Pragma("unroll") for (int m = 0; m < 4; ++m) _Pragma("unroll") for (int k = 0; k < 2; ++k) dst[m][k] = *(const PG8_LAS bf16x8*)(lds + PG8_SA(b, h) + aoff + m * 2048 + k * 1024); } while (0)
; #define PG8_LDB(dst, b, h) do { _Pragma("unroll") for (int n = 0; n < 2; ++n) _Pragma("unroll") for (int k = 0; k < 2; ++k) dst[n][k] = *(const PG8_LAS bf16x8*)(lds + PG8_SB(b, h) + boff + n * 2048 + k * 1024); } while (0)
; #define PG8_MMA(ai, bj, At, Bt) do { __builtin_amdgcn_s_setprio(1); _Pragma("unroll") for (int m = 0; m < 4; ++m) _Pragma("unroll") for (int n = 0; n < 2; ++n) _Pragma("unroll") for (int k = 0; k < 2; ++k) \
;         acc[ai][bj][m][n] = __builtin_amdgcn_mfma_f32_16x16x32_bf16(Bt[n][k], At[m][k], acc[ai][bj][m][n], 0, 0, 0); __builtin_amdgcn_s_setprio(0); } while (0)
; #define PG8_WAIT_V(n) asm volatile("s_waitcnt vmcnt(" #n ")" ::: "memory")
; #define PG8_WAIT_L(n) asm volatile("s_waitcnt lgkmcnt(" #n ")" ::: "memory")
; #define PG8_BAR __builtin_amdgcn_s_barrier()
; #define PG8_SCHED __builtin_amdgcn_sched_barrier(0)
; template <class Epi, class Sched, bool ALIGN_EPI = false, bool SP2 = false>
; __device__ __forceinline__ void gemm_phase(PG8_LAS unsigned char* lds, const Gemm g, const Sched& S, const Epi& E) {
;     ...
;             PG8_WAIT_V(8); PG8_WAIT_L(0); PG8_BAR; PG8_MMA(1, 0, At, B0); PG8_MMA(1, 1, At, B1); PG8_BAR; PG8_SCHED;
;             PG8_LDB(B0, 1, 0); PG8_LDB(B1, 1, 1); PG8_SCHED; PG8_LDA(At, 1, 0); PG8_STAGE(PG8_SA(0, 1), a2 + hstep, voffA);
;             PG8_WAIT_V(8); PG8_WAIT_L(0); PG8_BAR; PG8_MMA(0, 0, At, B0); PG8_MMA(0, 1, At, B1); PG8_BAR; PG8_SCHED;
	s_setprio 1
	s_waitcnt lgkmcnt(0)
	v_mfma_f32_16x16x32_bf16 v[60:63], v[140:143], v[200:203], v[60:63]
	v_mfma_f32_16x16x32_bf16 v[56:59], v[160:163], v[200:203], v[56:59]
	v_mfma_f32_16x16x32_bf16 v[44:47], v[140:143], v[208:211], v[44:47]
	v_mfma_f32_16x16x32_bf16 v[40:43], v[160:163], v[208:211], v[40:43]
	v_mfma_f32_16x16x32_bf16 v[28:31], v[140:143], v[216:219], v[28:31]
	v_mfma_f32_16x16x32_bf16 v[24:27], v[160:163], v[216:219], v[24:27]
	v_mfma_f32_16x16x32_bf16 v[12:15], v[140:143], v[224:227], v[12:15]
	v_mfma_f32_16x16x32_bf16 v[8:11], v[160:163], v[224:227], v[8:11]
	v_mfma_f32_16x16x32_bf16 v[60:63], v[156:159], v[204:207], v[60:63]
	v_mfma_f32_16x16x32_bf16 v[56:59], v[164:167], v[204:207], v[56:59]
	v_mfma_f32_16x16x32_bf16 v[44:47], v[156:159], v[212:215], v[44:47]
	v_mfma_f32_16x16x32_bf16 v[40:43], v[164:167], v[212:215], v[40:43]
	v_mfma_f32_16x16x32_bf16 v[28:31], v[156:159], v[220:223], v[28:31]
	v_mfma_f32_16x16x32_bf16 v[24:27], v[164:167], v[220:223], v[24:27]
	v_mfma_f32_16x16x32_bf16 v[12:15], v[156:159], v[228:231], v[12:15]
	v_mfma_f32_16x16x32_bf16 v[8:11], v[164:167], v[228:231], v[8:11]
	s_setprio 0
	s_setprio 1
	v_mfma_f32_16x16x32_bf16 v[52:55], v[168:171], v[200:203], v[52:55]
	v_mfma_f32_16x16x32_bf16 v[48:51], v[192:195], v[200:203], v[48:51]
	v_mfma_f32_16x16x32_bf16 v[36:39], v[168:171], v[208:211], v[36:39]
	v_mfma_f32_16x16x32_bf16 v[32:35], v[192:195], v[208:211], v[32:35]
	v_mfma_f32_16x16x32_bf16 v[20:23], v[168:171], v[216:219], v[20:23]
	v_mfma_f32_16x16x32_bf16 v[16:19], v[192:195], v[216:219], v[16:19]
	v_mfma_f32_16x16x32_bf16 v[4:7], v[168:171], v[224:227], v[4:7]
	v_mfma_f32_16x16x32_bf16 v[0:3], v[192:195], v[224:227], v[0:3]
	v_mfma_f32_16x16x32_bf16 v[52:55], v[172:175], v[204:207], v[52:55]
	v_mfma_f32_16x16x32_bf16 v[48:51], v[196:199], v[204:207], v[48:51]
	v_mfma_f32_16x16x32_bf16 v[36:39], v[172:175], v[212:215], v[36:39]
	v_mfma_f32_16x16x32_bf16 v[32:35], v[196:199], v[212:215], v[32:35]
	v_mfma_f32_16x16x32_bf16 v[20:23], v[172:175], v[220:223], v[20:23]
	v_mfma_f32_16x16x32_bf16 v[16:19], v[196:199], v[220:223], v[16:19]
	v_mfma_f32_16x16x32_bf16 v[4:7], v[172:175], v[228:231], v[4:7]
	v_mfma_f32_16x16x32_bf16 v[0:3], v[196:199], v[228:231], v[0:3]
	s_setprio 0
	s_barrier
	v_add_u32_e32 v144, s93, v147
	s_add_i32 s82, 0, 0x1c000
	ds_read_b128 v[140:143], v144
	ds_read_b128 v[156:159], v144 offset:1024
	ds_read_b128 v[160:163], v144 offset:2048
	ds_read_b128 v[164:167], v144 offset:3072
	v_add_u32_e32 v144, s82, v147
	ds_read_b128 v[168:171], v144
	ds_read_b128 v[172:175], v144 offset:1024
	ds_read_b128 v[192:195], v144 offset:2048
	ds_read_b128 v[196:199], v144 offset:3072
	s_add_u32 s68, s80, 0x80000
	s_addc_u32 s69, s81, 0
	s_mov_b32 m0, s16
	v_lshl_add_u64 v[190:191], s[68:69], 0, v[132:133]
	ds_read_b128 v[200:203], v149 offset:32768
	ds_read_b128 v[204:207], v149 offset:33792
	ds_read_b128 v[208:211], v149 offset:34816
	ds_read_b128 v[212:215], v149 offset:35840
	ds_read_b128 v[216:219], v149 offset:36864
	ds_read_b128 v[220:223], v149 offset:37888
	ds_read_b128 v[224:227], v149 offset:38912
	ds_read_b128 v[228:231], v149 offset:39936
	global_load_lds_dwordx4 v[190:191], off
	v_lshl_add_u64 v[190:191], s[68:69], 0, v[130:131]
	s_mov_b32 m0, s17
	s_nop 0
	global_load_lds_dwordx4 v[190:191], off
	s_waitcnt vmcnt(8)
	s_waitcnt lgkmcnt(0)
	s_barrier
	s_setprio 1
	s_waitcnt lgkmcnt(0)
	v_mfma_f32_16x16x32_bf16 v[124:127], v[140:143], v[200:203], v[124:127]
	v_mfma_f32_16x16x32_bf16 v[120:123], v[160:163], v[200:203], v[120:123]
	v_mfma_f32_16x16x32_bf16 v[108:111], v[140:143], v[208:211], v[108:111]
	v_mfma_f32_16x16x32_bf16 v[104:107], v[160:163], v[208:211], v[104:107]
	v_mfma_f32_16x16x32_bf16 v[92:95], v[140:143], v[216:219], v[92:95]
	v_mfma_f32_16x16x32_bf16 v[88:91], v[160:163], v[216:219], v[88:91]
	v_mfma_f32_16x16x32_bf16 v[76:79], v[140:143], v[224:227], v[76:79]
	v_mfma_f32_16x16x32_bf16 v[72:75], v[160:163], v[224:227], v[72:75]
	v_mfma_f32_16x16x32_bf16 v[124:127], v[156:159], v[204:207], v[124:127]
	v_mfma_f32_16x16x32_bf16 v[120:123], v[164:167], v[204:207], v[120:123]
	v_mfma_f32_16x16x32_bf16 v[108:111], v[156:159], v[212:215], v[108:111]
	v_mfma_f32_16x16x32_bf16 v[104:107], v[164:167], v[212:215], v[104:107]
	v_mfma_f32_16x16x32_bf16 v[92:95], v[156:159], v[220:223], v[92:95]
	v_mfma_f32_16x16x32_bf16 v[88:91], v[164:167], v[220:223], v[88:91]
	v_mfma_f32_16x16x32_bf16 v[76:79], v[156:159], v[228:231], v[76:79]
	v_mfma_f32_16x16x32_bf16 v[72:75], v[164:167], v[228:231], v[72:75]
	s_setprio 0
	s_setprio 1
	v_mfma_f32_16x16x32_bf16 v[116:119], v[168:171], v[200:203], v[116:119]
	v_mfma_f32_16x16x32_bf16 v[112:115], v[192:195], v[200:203], v[112:115]
	v_mfma_f32_16x16x32_bf16 v[100:103], v[168:171], v[208:211], v[100:103]
	v_mfma_f32_16x16x32_bf16 v[96:99], v[192:195], v[208:211], v[96:99]
	v_mfma_f32_16x16x32_bf16 v[84:87], v[168:171], v[216:219], v[84:87]
	v_mfma_f32_16x16x32_bf16 v[80:83], v[192:195], v[216:219], v[80:83]
	v_mfma_f32_16x16x32_bf16 v[68:71], v[168:171], v[224:227], v[68:71]
	v_mfma_f32_16x16x32_bf16 v[64:67], v[192:195], v[224:227], v[64:67]
	v_mfma_f32_16x16x32_bf16 v[116:119], v[172:175], v[204:207], v[116:119]
	v_mfma_f32_16x16x32_bf16 v[112:115], v[196:199], v[204:207], v[112:115]
	v_mfma_f32_16x16x32_bf16 v[100:103], v[172:175], v[212:215], v[100:103]
	v_mfma_f32_16x16x32_bf16 v[96:99], v[196:199], v[212:215], v[96:99]
	v_mfma_f32_16x16x32_bf16 v[84:87], v[172:175], v[220:223], v[84:87]
	v_mfma_f32_16x16x32_bf16 v[80:83], v[196:199], v[220:223], v[80:83]
	v_mfma_f32_16x16x32_bf16 v[68:71], v[172:175], v[228:231], v[68:71]
	v_mfma_f32_16x16x32_bf16 v[64:67], v[196:199], v[228:231], v[64:67]
	s_setprio 0
	s_barrier
; #define PG8_LDA(dst, b, h) do { _Pragma("unroll") for (int m = 0; m < 4; ++m) _Pragma("unroll") for (int k = 0; k < 2; ++k) dst[m][k] = *(const PG8_LAS bf16x8*)(lds + PG8_SA(b, h) + aoff + m * 2048 + k * 1024); } while (0)
; __device__ __forceinline__ float row_rs(const float* ssq, int row, int fq) {
;     const f32x4 a = *(const f32x4*)(ssq + (size_t)row * 32 + fq * 8), b = *(const f32x4*)(ssq + (size_t)row * 32 + fq * 8 + 4);
;     float s = ((a[0] + a[1]) + (a[2] + a[3])) + ((b[0] + b[1]) + (b[2] + b[3]));
;     s += __shfl_xor(s, 16); s += __shfl_xor(s, 32);
; template <class Epi, class Sched, bool ALIGN_EPI = false, bool SP2 = false>
; __device__ __forceinline__ void gemm_phase(PG8_LAS unsigned char* lds, const Gemm g, const Sched& S, const Epi& E) {
;     ...
;             PG8_LDA(At, 1, 1); PG8_STAGE(PG8_SB(1, 0), b3, voffB); PG8_STAGE(PG8_SB(1, 1), b3 + hstep, voffB); PG8_STAGE(PG8_SA(1, 0), a3, voffA);
;             PG8_WAIT_V(8); PG8_WAIT_L(0); PG8_BAR; PG8_MMA(1, 0, At, B0); PG8_MMA(1, 1, At, B1); PG8_BAR; PG8_SCHED;
;             } else {
;             PG8_LDB(B0, 0, 0); PG8_SCHED; PG8_LDA(At, 0, 0); PG8_STAGE(PG8_SA(1, 1), a1 + hstep, voffA);
;             PG8_WAIT_L(8); PG8_BAR; PG8_WAIT_L(0); PG8_MMA(0, 0, At, B0); PG8_BAR; PG8_SCHED;
;             PG8_LDB(B1, 0, 1); PG8_STAGE(PG8_SB(0, 0), b2, voffB);
;             PG8_BAR; PG8_WAIT_L(0); PG8_MMA(0, 1, At, B1); PG8_BAR;
;             PG8_LDA(At, 0, 1); PG8_STAGE(PG8_SA(0, 0), a2, voffA);
;             PG8_BAR; PG8_WAIT_L(0); PG8_MMA(1, 0, At, B0); PG8_BAR; PG8_SCHED;
;             PG8_STAGE(PG8_SB(0, 1), b2 + hstep, voffB);
;             PG8_WAIT_V(6); PG8_BAR; PG8_MMA(1, 1, At, B1); PG8_BAR;
;             PG8_LDB(B0, 1, 0); PG8_SCHED; PG8_LDA(At, 1, 0); PG8_STAGE(PG8_SA(0, 1), a2 + hstep, voffA);
;             PG8_WAIT_L(8); PG8_BAR; PG8_WAIT_L(0); PG8_MMA(0, 0, At, B0); PG8_BAR; PG8_SCHED;
;             PG8_LDB(B1, 1, 1); PG8_STAGE(PG8_SB(1, 0), b3, voffB);
;             PG8_BAR; PG8_WAIT_L(0); PG8_MMA(0, 1, At, B1); PG8_BAR;
;             PG8_LDA(At, 1, 1); PG8_STAGE(PG8_SA(1, 0), a3, voffA);
;             PG8_BAR; PG8_WAIT_L(0); PG8_MMA(1, 0, At, B0); PG8_BAR; PG8_SCHED;
;             PG8_STAGE(PG8_SB(1, 1), b3 + hstep, voffB);
;             PG8_WAIT_V(6); PG8_BAR; PG8_MMA(1, 1, At, B1); PG8_BAR;
;             }
;         }
;         if constexpr (ALIGN_EPI) { if (wr == 0) PG8_BAR; }
	s_add_i32 s68, s93, s0
	v_lshl_add_u64 v[150:151], v[150:151], 0, s[18:19]
	s_mov_b32 m0, s68
	ds_read_b128 v[200:203], v149 offset:49152
	ds_read_b128 v[204:207], v149 offset:50176
	ds_read_b128 v[208:211], v149 offset:51200
	ds_read_b128 v[212:215], v149 offset:52224
	ds_read_b128 v[216:219], v149 offset:53248
	ds_read_b128 v[220:223], v149 offset:54272
	ds_read_b128 v[224:227], v149 offset:55296
	ds_read_b128 v[228:231], v149 offset:56320
	global_load_lds_dwordx4 v[150:151], off
	s_add_i32 m0, s68, 0x2000
	s_add_u32 s68, s78, 0x80080
	v_lshl_add_u64 v[150:151], v[182:183], 0, s[18:19]
	s_addc_u32 s69, s79, 0
	s_add_i32 s78, s82, s0
	global_load_lds_dwordx4 v[150:151], off
	v_lshl_add_u64 v[150:151], s[68:69], 0, v[152:153]
	s_mov_b32 m0, s78
	s_nop 0
	global_load_lds_dwordx4 v[150:151], off
	v_lshl_add_u64 v[150:151], s[68:69], 0, v[128:129]
	s_add_i32 m0, s78, 0x2000
	s_nop 0
	global_load_lds_dwordx4 v[150:151], off
	v_lshl_add_u64 v[150:151], v[184:185], 0, s[18:19]
	s_mov_b32 m0, s22
	s_nop 0
	global_load_lds_dwordx4 v[150:151], off
	v_lshl_add_u64 v[150:151], v[188:189], 0, s[18:19]
	s_mov_b32 m0, s23
	s_nop 0
	global_load_lds_dwordx4 v[150:151], off
	s_waitcnt vmcnt(8)
	s_waitcnt lgkmcnt(0)
	s_barrier
	s_setprio 1
	s_waitcnt lgkmcnt(0)
	v_mfma_f32_16x16x32_bf16 v[60:63], v[140:143], v[200:203], v[60:63]
	v_mfma_f32_16x16x32_bf16 v[56:59], v[160:163], v[200:203], v[56:59]
	v_mfma_f32_16x16x32_bf16 v[44:47], v[140:143], v[208:211], v[44:47]
	v_mfma_f32_16x16x32_bf16 v[40:43], v[160:163], v[208:211], v[40:43]
	v_mfma_f32_16x16x32_bf16 v[28:31], v[140:143], v[216:219], v[28:31]
	v_mfma_f32_16x16x32_bf16 v[24:27], v[160:163], v[216:219], v[24:27]
	v_mfma_f32_16x16x32_bf16 v[12:15], v[140:143], v[224:227], v[12:15]
	v_mfma_f32_16x16x32_bf16 v[8:11], v[160:163], v[224:227], v[8:11]
	v_mfma_f32_16x16x32_bf16 v[60:63], v[156:159], v[204:207], v[60:63]
	v_mfma_f32_16x16x32_bf16 v[56:59], v[164:167], v[204:207], v[56:59]
	v_mfma_f32_16x16x32_bf16 v[44:47], v[156:159], v[212:215], v[44:47]
	v_mfma_f32_16x16x32_bf16 v[40:43], v[164:167], v[212:215], v[40:43]
	v_mfma_f32_16x16x32_bf16 v[28:31], v[156:159], v[220:223], v[28:31]
	v_mfma_f32_16x16x32_bf16 v[24:27], v[164:167], v[220:223], v[24:27]
	v_mfma_f32_16x16x32_bf16 v[12:15], v[156:159], v[228:231], v[12:15]
	v_mfma_f32_16x16x32_bf16 v[8:11], v[164:167], v[228:231], v[8:11]
	s_setprio 0
	s_setprio 1
	v_mfma_f32_16x16x32_bf16 v[52:55], v[168:171], v[200:203], v[52:55]
	v_mfma_f32_16x16x32_bf16 v[48:51], v[192:195], v[200:203], v[48:51]
	v_mfma_f32_16x16x32_bf16 v[36:39], v[168:171], v[208:211], v[36:39]
	v_mfma_f32_16x16x32_bf16 v[32:35], v[192:195], v[208:211], v[32:35]
	v_mfma_f32_16x16x32_bf16 v[20:23], v[168:171], v[216:219], v[20:23]
	v_mfma_f32_16x16x32_bf16 v[16:19], v[192:195], v[216:219], v[16:19]
	v_mfma_f32_16x16x32_bf16 v[4:7], v[168:171], v[224:227], v[4:7]
	v_mfma_f32_16x16x32_bf16 v[0:3], v[192:195], v[224:227], v[0:3]
	v_mfma_f32_16x16x32_bf16 v[52:55], v[172:175], v[204:207], v[52:55]
	v_mfma_f32_16x16x32_bf16 v[48:51], v[196:199], v[204:207], v[48:51]
	v_mfma_f32_16x16x32_bf16 v[36:39], v[172:175], v[212:215], v[36:39]
	v_mfma_f32_16x16x32_bf16 v[32:35], v[196:199], v[212:215], v[32:35]
	v_mfma_f32_16x16x32_bf16 v[20:23], v[172:175], v[220:223], v[20:23]
	v_mfma_f32_16x16x32_bf16 v[16:19], v[196:199], v[220:223], v[16:19]
	v_mfma_f32_16x16x32_bf16 v[4:7], v[172:175], v[228:231], v[4:7]
	v_mfma_f32_16x16x32_bf16 v[0:3], v[196:199], v[228:231], v[0:3]
	s_setprio 0
	s_barrier
	s_add_i32 s71, s71, 2
	s_add_u32 s42, s42, 0x100
	s_addc_u32 s43, s43, 0
	s_add_u32 s59, s59, 0x100
	s_addc_u32 s63, s63, 0
	s_cmp_gt_u32 s71, 29
	s_cbranch_scc0 .LBB0_165
	s_andn2_b64 vcc, exec, s[36:37]
	s_cbranch_vccnz .Lp3_pre_skip
	v_lshl_add_u32 v184, s54, 8, v145
	v_cmp_lt_i32_e32 vcc, v179, v180
	v_lshlrev_b32_e32 v184, 7, v184
	v_mov_b32_e32 v185, 0
	v_cndmask_b32_e32 v182, v178, v179, vcc
	v_cmp_lt_i32_e32 vcc, v187, v180
	v_lshl_add_u64 v[184:185], v[184:185], 0, v[134:135]
	v_mov_b32_e32 v154, 0x1000
	v_cndmask_b32_e32 v183, v178, v187, vcc
	v_mov_b32_e32 v155, 0
	v_lshlrev_b32_e32 v182, 2, v182
	v_lshlrev_b32_e32 v183, 2, v183
	global_load_dwordx4 v[164:167], v[184:185], off
	global_load_dwordx4 v[168:171], v[184:185], off offset:16
	global_load_dwordx4 v[172:175], v[184:185], off offset:2048
	global_load_dwordx4 v[188:191], v[184:185], off offset:2064
	v_lshl_add_u64 v[184:185], v[184:185], 0, v[154:155]
	v_mov_b32_e32 v154, 0x3000
	global_load_dwordx4 v[192:195], v[184:185], off
	global_load_dwordx4 v[196:199], v[184:185], off offset:16
	global_load_dwordx4 v[200:203], v[184:185], off offset:2048
	global_load_dwordx4 v[204:207], v[184:185], off offset:2064
	v_lshl_add_u64 v[184:185], v[184:185], 0, v[154:155]
	v_mov_b32_e32 v154, 0x1000
	global_load_dwordx4 v[208:211], v[184:185], off
	global_load_dwordx4 v[212:215], v[184:185], off offset:16
	global_load_dwordx4 v[216:219], v[184:185], off offset:2048
	global_load_dwordx4 v[220:223], v[184:185], off offset:2064
	v_lshl_add_u64 v[184:185], v[184:185], 0, v[154:155]
	global_load_dwordx4 v[224:227], v[184:185], off
	global_load_dwordx4 v[228:231], v[184:185], off offset:16
	global_load_dwordx4 v[232:235], v[184:185], off offset:2048
	global_load_dwordx4 v[248:251], v[184:185], off offset:2064
.Lp3_pre_skip:
	s_and_b64 vcc, exec, s[24:25]
	s_cbranch_vccz .LBB0_168
	s_barrier
; __device__ __forceinline__ unsigned cvt_pk_bf16(float lo, float hi) { unsigned r; asm volatile("v_cvt_pk_bf16_f32 %0, %1, %2" : "=v"(r) : "v"(lo), "v"(hi)); return r; }
; __device__ __forceinline__ float row_rs(const float* ssq, int row, int fq) {
;     const f32x4 a = *(const f32x4*)(ssq + (size_t)row * 32 + fq * 8), b = *(const f32x4*)(ssq + (size_t)row * 32 + fq * 8 + 4);
;     float s = ((a[0] + a[1]) + (a[2] + a[3])) + ((b[0] + b[1]) + (b[2] + b[3]));
;     s += __shfl_xor(s, 16); s += __shfl_xor(s, 32);
;     return __builtin_amdgcn_rsqf(s * (1.0f / 2048.0f) + 1e-6f);
;     __device__ __forceinline__ void operator()(const f32x4 (&acc)[2][2][4][2], const Unit& u, int wr, int wc, int fr, int fq) const {
;     ...
;             for (int m = 0; m < 4; ++m) { const int row = row0 + ai * HALF + m * 16; const float rs = ssq ? row_rs(ssq, row, fq) : 1.0f;
; #pragma unroll
;                 for (int bj = 0; bj < 2; ++bj) { const f32x4 v0 = acc[ai][bj][m][0] * rs, v1 = acc[ai][bj][m][1] * rs;
;                     u32x4 w; w.x = cvt_pk_bf16(v0[0], v0[1]); w.y = cvt_pk_bf16(v0[2], v0[3]); w.z = cvt_pk_bf16(v1[0], v1[1]); w.w = cvt_pk_bf16(v1[2], v1[3]);
;                     *(u32x4*)(O + (size_t)row * ldc + col0 + bj * HALF) = w; } }
.LBB0_168:
	s_andn2_b64 vcc, exec, s[36:37]
	s_cbranch_vccnz .Lp3_post_skip
	s_waitcnt vmcnt(14)
	v_add_f32_e32 v164, v164, v165
	v_add_f32_e32 v166, v166, v167
	v_add_f32_e32 v168, v168, v169
	v_add_f32_e32 v170, v170, v171
	v_add_f32_e32 v164, v164, v166
	v_add_f32_e32 v168, v168, v170
	v_add_f32_e32 v239, v164, v168
	ds_bpermute_b32 v164, v182, v239
	s_waitcnt vmcnt(12)
	v_add_f32_e32 v172, v172, v173
	v_add_f32_e32 v174, v174, v175
	v_add_f32_e32 v188, v188, v189
	v_add_f32_e32 v190, v190, v191
	v_add_f32_e32 v172, v172, v174
	v_add_f32_e32 v188, v188, v190
	v_add_f32_e32 v240, v172, v188
	ds_bpermute_b32 v165, v182, v240
	s_waitcnt vmcnt(10)
	v_add_f32_e32 v192, v192, v193
	v_add_f32_e32 v194, v194, v195
	v_add_f32_e32 v196, v196, v197
	v_add_f32_e32 v198, v198, v199
	v_add_f32_e32 v192, v192, v194
	v_add_f32_e32 v196, v196, v198
	v_add_f32_e32 v241, v192, v196
	ds_bpermute_b32 v166, v182, v241
	s_waitcnt vmcnt(8)
	v_add_f32_e32 v200, v200, v201
	v_add_f32_e32 v202, v202, v203
	v_add_f32_e32 v204, v204, v205
	v_add_f32_e32 v206, v206, v207
	v_add_f32_e32 v200, v200, v202
	v_add_f32_e32 v204, v204, v206
	v_add_f32_e32 v242, v200, v204
	ds_bpermute_b32 v167, v182, v242
	s_waitcnt vmcnt(6)
	v_add_f32_e32 v208, v208, v209
	v_add_f32_e32 v210, v210, v211
	v_add_f32_e32 v212, v212, v213
	v_add_f32_e32 v214, v214, v215
	v_add_f32_e32 v208, v208, v210
	v_add_f32_e32 v212, v212, v214
	v_add_f32_e32 v243, v208, v212
	ds_bpermute_b32 v168, v182, v243
	s_waitcnt vmcnt(4)
	v_add_f32_e32 v216, v216, v217
	v_add_f32_e32 v218, v218, v219
	v_add_f32_e32 v220, v220, v221
	v_add_f32_e32 v222, v222, v223
	v_add_f32_e32 v216, v216, v218
	v_add_f32_e32 v220, v220, v222
	v_add_f32_e32 v244, v216, v220
	ds_bpermute_b32 v169, v182, v244
	s_waitcnt vmcnt(2)
	v_add_f32_e32 v224, v224, v225
	v_add_f32_e32 v226, v226, v227
	v_add_f32_e32 v228, v228, v229
	v_add_f32_e32 v230, v230, v231
	v_add_f32_e32 v224, v224, v226
	v_add_f32_e32 v228, v228, v230
	v_add_f32_e32 v245, v224, v228
	ds_bpermute_b32 v170, v182, v245
	s_waitcnt vmcnt(0)
	v_add_f32_e32 v232, v232, v233
	v_add_f32_e32 v234, v234, v235
	v_add_f32_e32 v248, v248, v249
	v_add_f32_e32 v250, v250, v251
	v_add_f32_e32 v232, v232, v234
	v_add_f32_e32 v248, v248, v250
	v_add_f32_e32 v246, v232, v248
	ds_bpermute_b32 v171, v182, v246
	s_waitcnt lgkmcnt(7)
	v_add_f32_e32 v239, v239, v164
	ds_bpermute_b32 v164, v183, v239
	s_waitcnt lgkmcnt(7)
	v_add_f32_e32 v240, v240, v165
	ds_bpermute_b32 v165, v183, v240
	s_waitcnt lgkmcnt(7)
	v_add_f32_e32 v241, v241, v166
	ds_bpermute_b32 v166, v183, v241
	s_waitcnt lgkmcnt(7)
	v_add_f32_e32 v242, v242, v167
	ds_bpermute_b32 v167, v183, v242
	s_waitcnt lgkmcnt(7)
	v_add_f32_e32 v243, v243, v168
	ds_bpermute_b32 v168, v183, v243
	s_waitcnt lgkmcnt(7)
	v_add_f32_e32 v244, v244, v169
	ds_bpermute_b32 v169, v183, v244
	s_waitcnt lgkmcnt(7)
	v_add_f32_e32 v245, v245, v170
	ds_bpermute_b32 v170, v183, v245
	s_waitcnt lgkmcnt(7)
	v_add_f32_e32 v246, v246, v171
	ds_bpermute_b32 v171, v183, v246
	s_waitcnt lgkmcnt(7)
	v_add_f32_e32 v239, v239, v164
	s_waitcnt lgkmcnt(6)
	v_add_f32_e32 v240, v240, v165
	s_waitcnt lgkmcnt(5)
	v_add_f32_e32 v241, v241, v166
	s_waitcnt lgkmcnt(4)
	v_add_f32_e32 v242, v242, v167
	s_waitcnt lgkmcnt(3)
	v_add_f32_e32 v243, v243, v168
	s_waitcnt lgkmcnt(2)
	v_add_f32_e32 v244, v244, v169
	s_waitcnt lgkmcnt(1)
	v_add_f32_e32 v245, v245, v170
	s_waitcnt lgkmcnt(0)
	v_add_f32_e32 v246, v246, v171
	v_fmamk_f32 v239, v239, 0x3a000000, v177
	v_fmamk_f32 v240, v240, 0x3a000000, v177
	v_fmamk_f32 v241, v241, 0x3a000000, v177
	v_fmamk_f32 v242, v242, 0x3a000000, v177
	v_fmamk_f32 v243, v243, 0x3a000000, v177
	v_fmamk_f32 v244, v244, 0x3a000000, v177
	v_fmamk_f32 v245, v245, 0x3a000000, v177
	v_fmamk_f32 v246, v246, 0x3a000000, v177
	v_rsq_f32_e32 v239, v239
	v_rsq_f32_e32 v240, v240
	v_rsq_f32_e32 v241, v241
	v_rsq_f32_e32 v242, v242
	v_rsq_f32_e32 v243, v243
	v_rsq_f32_e32 v244, v244
	v_rsq_f32_e32 v245, v245
	v_rsq_f32_e32 v246, v246
	s_nop 0
.Lp3_post_skip:
	v_lshl_add_u32 v142, s54, 8, v145
	v_cndmask_b32_e64 v140, 0, 1, s[36:37]
	v_ashrrev_i32_e32 v143, 31, v142
	v_mov_b32_e32 v144, 1.0
	v_cmp_ne_u32_e64 s[42:43], 1, v140
	s_andn2_b64 vcc, exec, s[36:37]
	v_mov_b32_e32 v146, 1.0
	s_movk_i32 s58, 0x5fe
	s_movk_i32 s59, 0x1810
	s_cbranch_vccnz .LBB0_170
	v_mov_b32_e32 v146, v239
.LBB0_170:
	s_nop 0
	v_pk_mul_f32 v[124:125], v[124:125], v[146:147] op_sel_hi:[1,0]
	v_lshl_or_b32 v140, s34, 8, v148
	v_pk_mul_f32 v[150:151], v[122:123], v[146:147] op_sel_hi:[1,0]
	v_pk_mul_f32 v[122:123], v[120:121], v[146:147] op_sel_hi:[1,0]
	v_cvt_pk_bf16_f32 v120, v124, v125
	v_mov_b64_e32 v[124:125], s[38:39]
	v_ashrrev_i32_e32 v141, 31, v140
	v_mad_i64_i32 v[124:125], s[54:55], v142, s97, v[124:125]
	v_pk_mul_f32 v[126:127], v[126:127], v[146:147] op_sel_hi:[1,0]
	v_lshl_add_u64 v[124:125], v[140:141], 1, v[124:125]
	v_cvt_pk_bf16_f32 v121, v126, v127
	v_cvt_pk_bf16_f32 v122, v122, v123
	v_cvt_pk_bf16_f32 v123, v150, v151
	global_store_dwordx4 v[124:125], v[120:123], off
	v_pk_mul_f32 v[116:117], v[116:117], v[146:147] op_sel_hi:[1,0]
	v_pk_mul_f32 v[118:119], v[118:119], v[146:147] op_sel_hi:[1,0]
	v_pk_mul_f32 v[120:121], v[114:115], v[146:147] op_sel_hi:[1,0]
	v_pk_mul_f32 v[114:115], v[112:113], v[146:147] op_sel_hi:[1,0]
	v_cvt_pk_bf16_f32 v112, v116, v117
	v_cvt_pk_bf16_f32 v113, v118, v119
	s_and_b64 vcc, exec, s[42:43]
	v_cvt_pk_bf16_f32 v114, v114, v115
	v_cvt_pk_bf16_f32 v115, v120, v121
	global_store_dwordx4 v[124:125], v[112:115], off offset:256
	s_nop 1
	v_or_b32_e32 v112, 16, v142
	v_ashrrev_i32_e32 v113, 31, v112
	s_cbranch_vccnz .LBB0_172
	v_mov_b32_e32 v144, v240
; __device__ __forceinline__ unsigned cvt_pk_bf16(float lo, float hi) { unsigned r; asm volatile("v_cvt_pk_bf16_f32 %0, %1, %2" : "=v"(r) : "v"(lo), "v"(hi)); return r; }
; __device__ __forceinline__ float row_rs(const float* ssq, int row, int fq) {
;     const f32x4 a = *(const f32x4*)(ssq + (size_t)row * 32 + fq * 8), b = *(const f32x4*)(ssq + (size_t)row * 32 + fq * 8 + 4);
;     float s = ((a[0] + a[1]) + (a[2] + a[3])) + ((b[0] + b[1]) + (b[2] + b[3]));
;     s += __shfl_xor(s, 16); s += __shfl_xor(s, 32);
;     return __builtin_amdgcn_rsqf(s * (1.0f / 2048.0f) + 1e-6f);
;     __device__ __forceinline__ void operator()(const f32x4 (&acc)[2][2][4][2], const Unit& u, int wr, int wc, int fr, int fq) const {
;     ...
;             for (int m = 0; m < 4; ++m) { const int row = row0 + ai * HALF + m * 16; const float rs = ssq ? row_rs(ssq, row, fq) : 1.0f;
; #pragma unroll
;                 for (int bj = 0; bj < 2; ++bj) { const f32x4 v0 = acc[ai][bj][m][0] * rs, v1 = acc[ai][bj][m][1] * rs;
;                     u32x4 w; w.x = cvt_pk_bf16(v0[0], v0[1]); w.y = cvt_pk_bf16(v0[2], v0[3]); w.z = cvt_pk_bf16(v1[0], v1[1]); w.w = cvt_pk_bf16(v1[2], v1[3]);
;                     *(u32x4*)(O + (size_t)row * ldc + col0 + bj * HALF) = w; } }
.LBB0_172:
	s_nop 0
	v_pk_mul_f32 v[108:109], v[108:109], v[144:145] op_sel_hi:[1,0]
	v_pk_mul_f32 v[114:115], v[106:107], v[144:145] op_sel_hi:[1,0]
	v_pk_mul_f32 v[106:107], v[104:105], v[144:145] op_sel_hi:[1,0]
	v_cvt_pk_bf16_f32 v104, v108, v109
	v_mov_b64_e32 v[108:109], s[38:39]
	v_mad_i64_i32 v[108:109], s[54:55], v112, s97, v[108:109]
	v_pk_mul_f32 v[110:111], v[110:111], v[144:145] op_sel_hi:[1,0]
	v_lshl_add_u64 v[108:109], v[140:141], 1, v[108:109]
	v_cvt_pk_bf16_f32 v105, v110, v111
	v_cvt_pk_bf16_f32 v106, v106, v107
	v_cvt_pk_bf16_f32 v107, v114, v115
	global_store_dwordx4 v[108:109], v[104:107], off
	v_pk_mul_f32 v[102:103], v[102:103], v[144:145] op_sel_hi:[1,0]
	v_pk_mul_f32 v[100:101], v[100:101], v[144:145] op_sel_hi:[1,0]
	v_pk_mul_f32 v[104:105], v[98:99], v[144:145] op_sel_hi:[1,0]
	v_pk_mul_f32 v[98:99], v[96:97], v[144:145] op_sel_hi:[1,0]
	v_cvt_pk_bf16_f32 v96, v100, v101
	v_cvt_pk_bf16_f32 v97, v102, v103
	s_and_b64 vcc, exec, s[42:43]
	v_cvt_pk_bf16_f32 v98, v98, v99
	v_cvt_pk_bf16_f32 v99, v104, v105
	global_store_dwordx4 v[108:109], v[96:99], off offset:256
	v_mov_b32_e32 v100, 1.0
	s_movk_i32 s81, 0x77e
	v_or_b32_e32 v98, 32, v142
	v_ashrrev_i32_e32 v99, 31, v98
	v_mov_b32_e32 v96, 1.0
	s_cbranch_vccnz .LBB0_174
	v_mov_b32_e32 v100, v241
.LBB0_174:
	s_nop 0
	v_pk_mul_f32 v[92:93], v[92:93], v[100:101] op_sel_hi:[1,0]
	v_pk_mul_f32 v[102:103], v[90:91], v[100:101] op_sel_hi:[1,0]
	v_pk_mul_f32 v[90:91], v[88:89], v[100:101] op_sel_hi:[1,0]
	v_cvt_pk_bf16_f32 v88, v92, v93
	v_mov_b64_e32 v[92:93], s[38:39]
	v_mad_i64_i32 v[92:93], s[54:55], v98, s97, v[92:93]
	v_pk_mul_f32 v[94:95], v[94:95], v[100:101] op_sel_hi:[1,0]
	v_lshl_add_u64 v[92:93], v[140:141], 1, v[92:93]
	v_cvt_pk_bf16_f32 v89, v94, v95
	v_cvt_pk_bf16_f32 v90, v90, v91
	v_cvt_pk_bf16_f32 v91, v102, v103
	global_store_dwordx4 v[92:93], v[88:91], off
	v_pk_mul_f32 v[84:85], v[84:85], v[100:101] op_sel_hi:[1,0]
	v_pk_mul_f32 v[86:87], v[86:87], v[100:101] op_sel_hi:[1,0]
	v_pk_mul_f32 v[88:89], v[82:83], v[100:101] op_sel_hi:[1,0]
	v_pk_mul_f32 v[82:83], v[80:81], v[100:101] op_sel_hi:[1,0]
	v_cvt_pk_bf16_f32 v80, v84, v85
	v_cvt_pk_bf16_f32 v81, v86, v87
	s_and_b64 vcc, exec, s[42:43]
	v_cvt_pk_bf16_f32 v82, v82, v83
	v_cvt_pk_bf16_f32 v83, v88, v89
	global_store_dwordx4 v[92:93], v[80:83], off offset:256
	s_nop 1
	v_or_b32_e32 v80, 48, v142
	v_ashrrev_i32_e32 v81, 31, v80
	s_cbranch_vccnz .LBB0_176
	v_mov_b32_e32 v96, v242
.LBB0_176:
	s_nop 0
	v_pk_mul_f32 v[76:77], v[76:77], v[96:97] op_sel_hi:[1,0]
	v_pk_mul_f32 v[82:83], v[74:75], v[96:97] op_sel_hi:[1,0]
	v_pk_mul_f32 v[74:75], v[72:73], v[96:97] op_sel_hi:[1,0]
	v_cvt_pk_bf16_f32 v72, v76, v77
	v_mov_b64_e32 v[76:77], s[38:39]
	v_mad_i64_i32 v[76:77], s[54:55], v80, s97, v[76:77]
	v_pk_mul_f32 v[78:79], v[78:79], v[96:97] op_sel_hi:[1,0]
	v_lshl_add_u64 v[76:77], v[140:141], 1, v[76:77]
	v_cvt_pk_bf16_f32 v73, v78, v79
	v_cvt_pk_bf16_f32 v74, v74, v75
	v_cvt_pk_bf16_f32 v75, v82, v83
	global_store_dwordx4 v[76:77], v[72:75], off
	v_pk_mul_f32 v[70:71], v[70:71], v[96:97] op_sel_hi:[1,0]
	v_pk_mul_f32 v[68:69], v[68:69], v[96:97] op_sel_hi:[1,0]
	v_pk_mul_f32 v[72:73], v[66:67], v[96:97] op_sel_hi:[1,0]
	v_pk_mul_f32 v[66:67], v[64:65], v[96:97] op_sel_hi:[1,0]
	v_cvt_pk_bf16_f32 v64, v68, v69
	v_cvt_pk_bf16_f32 v65, v70, v71
	s_and_b64 vcc, exec, s[42:43]
	v_cvt_pk_bf16_f32 v66, v66, v67
	v_cvt_pk_bf16_f32 v67, v72, v73
	global_store_dwordx4 v[76:77], v[64:67], off offset:256
	v_mov_b32_e32 v68, 1.0
	s_nop 0
	v_add_u32_e32 v66, 0x80, v142
	v_ashrrev_i32_e32 v67, 31, v66
	v_mov_b32_e32 v64, 1.0
	s_cbranch_vccnz .LBB0_178
	v_mov_b32_e32 v68, v243
; __device__ __forceinline__ unsigned cvt_pk_bf16(float lo, float hi) { unsigned r; asm volatile("v_cvt_pk_bf16_f32 %0, %1, %2" : "=v"(r) : "v"(lo), "v"(hi)); return r; }
; __device__ __forceinline__ float row_rs(const float* ssq, int row, int fq) {
;     const f32x4 a = *(const f32x4*)(ssq + (size_t)row * 32 + fq * 8), b = *(const f32x4*)(ssq + (size_t)row * 32 + fq * 8 + 4);
;     float s = ((a[0] + a[1]) + (a[2] + a[3])) + ((b[0] + b[1]) + (b[2] + b[3]));
;     s += __shfl_xor(s, 16); s += __shfl_xor(s, 32);
;     return __builtin_amdgcn_rsqf(s * (1.0f / 2048.0f) + 1e-6f);
;     __device__ __forceinline__ void operator()(const f32x4 (&acc)[2][2][4][2], const Unit& u, int wr, int wc, int fr, int fq) const {
;     ...
;             for (int m = 0; m < 4; ++m) { const int row = row0 + ai * HALF + m * 16; const float rs = ssq ? row_rs(ssq, row, fq) : 1.0f;
; #pragma unroll
;                 for (int bj = 0; bj < 2; ++bj) { const f32x4 v0 = acc[ai][bj][m][0] * rs, v1 = acc[ai][bj][m][1] * rs;
;                     u32x4 w; w.x = cvt_pk_bf16(v0[0], v0[1]); w.y = cvt_pk_bf16(v0[2], v0[3]); w.z = cvt_pk_bf16(v1[0], v1[1]); w.w = cvt_pk_bf16(v1[2], v1[3]);
;                     *(u32x4*)(O + (size_t)row * ldc + col0 + bj * HALF) = w; } }
.LBB0_178:
	s_nop 0
	v_pk_mul_f32 v[60:61], v[60:61], v[68:69] op_sel_hi:[1,0]
	v_pk_mul_f32 v[70:71], v[58:59], v[68:69] op_sel_hi:[1,0]
	v_pk_mul_f32 v[58:59], v[56:57], v[68:69] op_sel_hi:[1,0]
	v_cvt_pk_bf16_f32 v56, v60, v61
	v_mov_b64_e32 v[60:61], s[38:39]
	v_mad_i64_i32 v[60:61], s[54:55], v66, s97, v[60:61]
	v_pk_mul_f32 v[62:63], v[62:63], v[68:69] op_sel_hi:[1,0]
	v_lshl_add_u64 v[60:61], v[140:141], 1, v[60:61]
	v_cvt_pk_bf16_f32 v57, v62, v63
	v_cvt_pk_bf16_f32 v58, v58, v59
	v_cvt_pk_bf16_f32 v59, v70, v71
	global_store_dwordx4 v[60:61], v[56:59], off
	v_pk_mul_f32 v[52:53], v[52:53], v[68:69] op_sel_hi:[1,0]
	v_pk_mul_f32 v[54:55], v[54:55], v[68:69] op_sel_hi:[1,0]
	v_pk_mul_f32 v[56:57], v[50:51], v[68:69] op_sel_hi:[1,0]
	v_pk_mul_f32 v[50:51], v[48:49], v[68:69] op_sel_hi:[1,0]
	v_cvt_pk_bf16_f32 v48, v52, v53
	v_cvt_pk_bf16_f32 v49, v54, v55
	s_and_b64 vcc, exec, s[42:43]
	v_cvt_pk_bf16_f32 v50, v50, v51
	v_cvt_pk_bf16_f32 v51, v56, v57
	global_store_dwordx4 v[60:61], v[48:51], off offset:256
	s_nop 1
	v_add_u32_e32 v48, 0x90, v142
	v_ashrrev_i32_e32 v49, 31, v48
	s_cbranch_vccnz .LBB0_180
	v_mov_b32_e32 v64, v244
.LBB0_180:
	s_nop 0
	v_pk_mul_f32 v[44:45], v[44:45], v[64:65] op_sel_hi:[1,0]
	v_pk_mul_f32 v[50:51], v[42:43], v[64:65] op_sel_hi:[1,0]
	v_pk_mul_f32 v[42:43], v[40:41], v[64:65] op_sel_hi:[1,0]
	v_cvt_pk_bf16_f32 v40, v44, v45
	v_mov_b64_e32 v[44:45], s[38:39]
	v_mad_i64_i32 v[44:45], s[54:55], v48, s97, v[44:45]
	v_pk_mul_f32 v[46:47], v[46:47], v[64:65] op_sel_hi:[1,0]
	v_lshl_add_u64 v[44:45], v[140:141], 1, v[44:45]
	v_cvt_pk_bf16_f32 v41, v46, v47
	v_cvt_pk_bf16_f32 v42, v42, v43
	v_cvt_pk_bf16_f32 v43, v50, v51
	global_store_dwordx4 v[44:45], v[40:43], off
	v_pk_mul_f32 v[38:39], v[38:39], v[64:65] op_sel_hi:[1,0]
	v_pk_mul_f32 v[36:37], v[36:37], v[64:65] op_sel_hi:[1,0]
	v_pk_mul_f32 v[40:41], v[34:35], v[64:65] op_sel_hi:[1,0]
	v_pk_mul_f32 v[34:35], v[32:33], v[64:65] op_sel_hi:[1,0]
	v_cvt_pk_bf16_f32 v32, v36, v37
	v_cvt_pk_bf16_f32 v33, v38, v39
	s_and_b64 vcc, exec, s[42:43]
	v_cvt_pk_bf16_f32 v34, v34, v35
	v_cvt_pk_bf16_f32 v35, v40, v41
	global_store_dwordx4 v[44:45], v[32:35], off offset:256
	v_mov_b32_e32 v36, 1.0
	s_nop 0
	v_add_u32_e32 v34, 0xa0, v142
	v_ashrrev_i32_e32 v35, 31, v34
	v_mov_b32_e32 v32, 1.0
	s_cbranch_vccnz .LBB0_182
	v_mov_b32_e32 v36, v245
.LBB0_182:
	s_nop 0
	v_pk_mul_f32 v[28:29], v[28:29], v[36:37] op_sel_hi:[1,0]
	v_pk_mul_f32 v[38:39], v[26:27], v[36:37] op_sel_hi:[1,0]
	v_pk_mul_f32 v[26:27], v[24:25], v[36:37] op_sel_hi:[1,0]
	v_cvt_pk_bf16_f32 v24, v28, v29
	v_mov_b64_e32 v[28:29], s[38:39]
	v_mad_i64_i32 v[28:29], s[54:55], v34, s97, v[28:29]
	v_pk_mul_f32 v[30:31], v[30:31], v[36:37] op_sel_hi:[1,0]
	v_lshl_add_u64 v[28:29], v[140:141], 1, v[28:29]
	v_cvt_pk_bf16_f32 v25, v30, v31
	v_cvt_pk_bf16_f32 v26, v26, v27
	v_cvt_pk_bf16_f32 v27, v38, v39
	global_store_dwordx4 v[28:29], v[24:27], off
	v_pk_mul_f32 v[20:21], v[20:21], v[36:37] op_sel_hi:[1,0]
	v_pk_mul_f32 v[22:23], v[22:23], v[36:37] op_sel_hi:[1,0]
	v_pk_mul_f32 v[24:25], v[18:19], v[36:37] op_sel_hi:[1,0]
	v_pk_mul_f32 v[18:19], v[16:17], v[36:37] op_sel_hi:[1,0]
	v_cvt_pk_bf16_f32 v16, v20, v21
	v_cvt_pk_bf16_f32 v17, v22, v23
	s_and_b64 vcc, exec, s[42:43]
	v_cvt_pk_bf16_f32 v18, v18, v19
	v_cvt_pk_bf16_f32 v19, v24, v25
	global_store_dwordx4 v[28:29], v[16:19], off offset:256
	s_nop 1
	v_add_u32_e32 v16, 0xb0, v142
	v_ashrrev_i32_e32 v17, 31, v16
	s_cbranch_vccnz .LBB0_184
	v_mov_b32_e32 v32, v246
